# proj tail strided by gridDim (any grid size); otherwise as v30
# speedup vs baseline: 1.0210x; 1.0044x over previous
.LBB0_197:
	s_load_dword s15, s[0:1], 0x120
	s_mov_b32 s14, s2
	s_waitcnt vmcnt(0) lgkmcnt(0)
.Lpt_loop:
	s_cmpk_gt_i32 s14, 0xff
	s_cbranch_scc1 .LBB0_426
	v_lshrrev_b32_e32 v0, 6, v204
	v_and_b32_e32 v1, 63, v204
	v_and_b32_e32 v2, 15, v1
	v_lshrrev_b32_e32 v3, 4, v1
	v_lshlrev_b32_e32 v4, 8, v0
	v_lshl_add_u32 v4, v3, 4, v4
	s_lshl_b32 s4, s14, 16
	v_lshl_add_u32 v5, v2, 11, v4
	v_add_u32_e32 v7, 0x400000, v5
	v_add_u32_e32 v5, s4, v5
	v_add_u32_e32 v6, 0x8000, v5
	v_add_u32_e32 v8, 0x8000, v7
	v_add_u32_e32 v9, 0x10000, v7
	s_add_u32 s6, s34, 0x8a44000
	s_addc_u32 s7, s35, 0
	global_load_dwordx4 v[16:19], v5, s[6:7]
	global_load_dwordx4 v[20:23], v5, s[6:7] offset:64
	global_load_dwordx4 v[24:27], v5, s[6:7] offset:128
	global_load_dwordx4 v[28:31], v5, s[6:7] offset:192
	global_load_dwordx4 v[32:35], v6, s[6:7]
	global_load_dwordx4 v[36:39], v6, s[6:7] offset:64
	global_load_dwordx4 v[40:43], v6, s[6:7] offset:128
	global_load_dwordx4 v[44:47], v6, s[6:7] offset:192
	global_load_dwordx4 v[48:51], v7, s[34:35]
	global_load_dwordx4 v[52:55], v7, s[34:35] offset:64
	global_load_dwordx4 v[56:59], v7, s[34:35] offset:128
	global_load_dwordx4 v[60:63], v7, s[34:35] offset:192
	global_load_dwordx4 v[64:67], v8, s[34:35]
	global_load_dwordx4 v[68:71], v8, s[34:35] offset:64
	global_load_dwordx4 v[72:75], v8, s[34:35] offset:128
	global_load_dwordx4 v[76:79], v8, s[34:35] offset:192
	global_load_dwordx4 v[80:83], v9, s[34:35]
	global_load_dwordx4 v[84:87], v9, s[34:35] offset:64
	global_load_dwordx4 v[88:91], v9, s[34:35] offset:128
	global_load_dwordx4 v[92:95], v9, s[34:35] offset:192
	v_mul_u32_u24_e32 v10, 0x1800, v0
	v_lshl_add_u32 v10, v1, 4, v10
	v_lshlrev_b32_e32 v11, 10, v0
	v_lshl_add_u32 v11, v1, 4, v11
	v_readfirstlane_b32 s5, v0
	s_waitcnt vmcnt(0)
	v_mfma_f32_16x16x32_bf16 v[96:99], v[16:19], v[48:51], 0
	v_mfma_f32_16x16x32_bf16 v[100:103], v[16:19], v[64:67], 0
	v_mfma_f32_16x16x32_bf16 v[104:107], v[16:19], v[80:83], 0
	v_mfma_f32_16x16x32_bf16 v[108:111], v[32:35], v[48:51], 0
	v_mfma_f32_16x16x32_bf16 v[112:115], v[32:35], v[64:67], 0
	v_mfma_f32_16x16x32_bf16 v[116:119], v[32:35], v[80:83], 0
	v_mfma_f32_16x16x32_bf16 v[96:99], v[20:23], v[52:55], v[96:99]
	v_mfma_f32_16x16x32_bf16 v[100:103], v[20:23], v[68:71], v[100:103]
	v_mfma_f32_16x16x32_bf16 v[104:107], v[20:23], v[84:87], v[104:107]
	v_mfma_f32_16x16x32_bf16 v[108:111], v[36:39], v[52:55], v[108:111]
	v_mfma_f32_16x16x32_bf16 v[112:115], v[36:39], v[68:71], v[112:115]
	v_mfma_f32_16x16x32_bf16 v[116:119], v[36:39], v[84:87], v[116:119]
	v_mfma_f32_16x16x32_bf16 v[96:99], v[24:27], v[56:59], v[96:99]
	v_mfma_f32_16x16x32_bf16 v[100:103], v[24:27], v[72:75], v[100:103]
	v_mfma_f32_16x16x32_bf16 v[104:107], v[24:27], v[88:91], v[104:107]
	v_mfma_f32_16x16x32_bf16 v[108:111], v[40:43], v[56:59], v[108:111]
	v_mfma_f32_16x16x32_bf16 v[112:115], v[40:43], v[72:75], v[112:115]
	v_mfma_f32_16x16x32_bf16 v[116:119], v[40:43], v[88:91], v[116:119]
	v_mfma_f32_16x16x32_bf16 v[96:99], v[28:31], v[60:63], v[96:99]
	v_mfma_f32_16x16x32_bf16 v[100:103], v[28:31], v[76:79], v[100:103]
	v_mfma_f32_16x16x32_bf16 v[104:107], v[28:31], v[92:95], v[104:107]
	v_mfma_f32_16x16x32_bf16 v[108:111], v[44:47], v[60:63], v[108:111]
	v_mfma_f32_16x16x32_bf16 v[112:115], v[44:47], v[76:79], v[112:115]
	v_mfma_f32_16x16x32_bf16 v[116:119], v[44:47], v[92:95], v[116:119]
	s_nop 7
	s_nop 3
	ds_write_b128 v10, v[96:99]
	ds_write_b128 v10, v[100:103] offset:1024
	ds_write_b128 v10, v[104:107] offset:2048
	ds_write_b128 v10, v[108:111] offset:3072
	ds_write_b128 v10, v[112:115] offset:4096
	ds_write_b128 v10, v[116:119] offset:5120
	s_waitcnt lgkmcnt(0)
	s_barrier
	s_cmp_gt_u32 s5, 5
	s_cbranch_scc1 .Lpt_done
	ds_read_b128 v[120:123], v11
	ds_read_b128 v[124:127], v11 offset:6144
	ds_read_b128 v[128:131], v11 offset:12288
	ds_read_b128 v[132:135], v11 offset:18432
	ds_read_b128 v[136:139], v11 offset:24576
	ds_read_b128 v[140:143], v11 offset:30720
	ds_read_b128 v[144:147], v11 offset:36864
	ds_read_b128 v[148:151], v11 offset:43008
	s_cmp_gt_u32 s5, 2
	s_cselect_b32 s8, 1, 0
	s_mul_i32 s9, s8, 3
	s_sub_u32 s9, s5, s9
	s_lshl_b32 s10, s14, 5
	s_lshl_b32 s11, s8, 4
	s_add_u32 s10, s10, s11
	v_lshl_add_u32 v12, v3, 2, s10
	s_waitcnt lgkmcnt(6)
	v_add_f32_e32 v120, v120, v124
	v_add_f32_e32 v121, v121, v125
	v_add_f32_e32 v122, v122, v126
	v_add_f32_e32 v123, v123, v127
	s_waitcnt lgkmcnt(5)
	v_add_f32_e32 v120, v120, v128
	v_add_f32_e32 v121, v121, v129
	v_add_f32_e32 v122, v122, v130
	v_add_f32_e32 v123, v123, v131
	s_waitcnt lgkmcnt(4)
	v_add_f32_e32 v120, v120, v132
	v_add_f32_e32 v121, v121, v133
	v_add_f32_e32 v122, v122, v134
	v_add_f32_e32 v123, v123, v135
	s_waitcnt lgkmcnt(3)
	v_add_f32_e32 v120, v120, v136
	v_add_f32_e32 v121, v121, v137
	v_add_f32_e32 v122, v122, v138
	v_add_f32_e32 v123, v123, v139
	s_waitcnt lgkmcnt(2)
	v_add_f32_e32 v120, v120, v140
	v_add_f32_e32 v121, v121, v141
	v_add_f32_e32 v122, v122, v142
	v_add_f32_e32 v123, v123, v143
	s_waitcnt lgkmcnt(1)
	v_add_f32_e32 v120, v120, v144
	v_add_f32_e32 v121, v121, v145
	v_add_f32_e32 v122, v122, v146
	v_add_f32_e32 v123, v123, v147
	s_waitcnt lgkmcnt(0)
	v_add_f32_e32 v120, v120, v148
	v_add_f32_e32 v121, v121, v149
	v_add_f32_e32 v122, v122, v150
	v_add_f32_e32 v123, v123, v151
	s_cmp_eq_u32 s9, 2
	s_cbranch_scc1 .Lpt_dt
	s_lshl_b32 s11, s9, 5
	s_add_u32 s11, s11, 0x28c5000
	s_add_u32 s12, s34, s11
	s_addc_u32 s13, s35, 0
	v_mul_u32_u24_e32 v13, 0x1040, v12
	v_lshl_add_u32 v13, v2, 1, v13
	v_cvt_pk_bf16_f32 v14, v120, v120
	global_store_short v13, v14, s[12:13]
	v_add_u32_e32 v13, 0x1040, v13
	v_cvt_pk_bf16_f32 v14, v121, v121
	global_store_short v13, v14, s[12:13]
	v_add_u32_e32 v13, 0x1040, v13
	v_cvt_pk_bf16_f32 v14, v122, v122
	global_store_short v13, v14, s[12:13]
	v_add_u32_e32 v13, 0x1040, v13
	v_cvt_pk_bf16_f32 v14, v123, v123
	global_store_short v13, v14, s[12:13]
	s_branch .Lpt_done

.Lpt_done:
	s_waitcnt lgkmcnt(0)
	s_barrier
	s_add_u32 s14, s14, s15
	s_branch .Lpt_loop
